# scans on all 8 waves of 68 workgroups spread evenly over the first-unit size classes (every 4th stream + 4 for S5); other workgroups start attention at once, queue scheduling evens it out
# speedup vs baseline: 1.0185x; 1.0030x over previous
; __global__ void __launch_bounds__(NWAVES * 64, 2) hymba_fwd(Args args) {
;     ...
;             unsigned* scnt = (unsigned*)(ws + WS_SCNT) + layer * 64;
;             { unsigned ndone = 0;
;               if (wave < 2) { for (int t2 = wave * G + vcu; t2 < 512; t2 += 2 * G) { hgrn_scan(pa, t2, lane); ++ndone; } }
;               else if (wave == 2) { for (int t2 = vcu; t2 < 32; t2 += G) { s5_scan(pa, layer, t2, lane); ++ndone; } }
;               if (ndone) { asm volatile("s_waitcnt vmcnt(0)" ::: "memory"); if (lane == 0) (void)__hip_atomic_fetch_add(scnt, ndone, __ATOMIC_RELAXED, __HIP_MEMORY_SCOPE_AGENT); } }
.LBB0_554:
	s_or_b64 exec, exec, s[0:1]
	s_waitcnt lgkmcnt(0)
	s_barrier
	s_mov_b32 s37, 0
	v_readlane_b32 s12, v253, 18
	v_readlane_b32 s0, v252, 0
	s_lshr_b32 s1, s0, 4
	s_and_b32 s3, s1, 3
	s_cmp_eq_u32 s3, 3
	s_cbranch_scc1 .Lmy_sc_hsel
	s_cmp_eq_u32 s3, 1
	s_cbranch_scc0 .LBB0_569
	s_and_b32 s3, s0, 15
	s_cmp_eq_u32 s3, 15
	s_cbranch_scc0 .LBB0_569
	s_lshr_b32 s3, s1, 2
	s_lshl_b32 s3, s3, 3
	s_add_i32 s3, s3, s36
	v_readlane_b32 s0, v254, 44
	s_lshl_b32 s38, s0, 12
	v_readlane_b32 s0, v252, 18
	v_writelane_b32 v255, s74, 7
	v_lshlrev_b32_e32 v220, 2, v140
	v_readlane_b32 s1, v252, 19
	v_writelane_b32 v255, s75, 8
	v_lshlrev_b32_e32 v2, 2, v140
	v_lshl_add_u64 v[0:1], s[0:1], 0, v[220:221]
	s_mov_b32 s39, s3
	s_branch .LBB0_557
.Lmy_sc_hsel:
	s_lshr_b32 s1, s1, 2
	s_lshl_b32 s1, s1, 4
	s_and_b32 s3, s0, 15
	s_or_b32 s1, s1, s3
	s_lshl_b32 s1, s1, 3
	s_add_i32 s2, s1, s36
	v_and_b32_e32 v6, 3, v141
	v_lshlrev_b32_e32 v220, 2, v140
	s_branch .LBB0_566
